# full stack + compact index keys also in the DSA level-1 radix pass
# speedup vs baseline: 1.0088x; 1.0088x over previous
; __device__ __forceinline__ void dsa_item(const KP& p, int b, int tile, char* smem) {
;     ...
;   auto loadk = [&](int kt, h8* a) __attribute__((always_inline)) {
; #pragma unroll
;     for (int i = 0; i < 2; ++i)
;       a[i] = *(const h8*)(ub + (size_t)(kt * 32 + i * 16 + (lane & 15)) * NU + C_IK + hq * 8);
;   };
;     ...
;       const unsigned long long mypfx = pfx[mytok];
;       const bool act = state[mytok] == 1 && fastf[mytok] == 0;
;       h8 na[2];
;       if (wid < nkt) loadk(wid, na);
.LBB0_927:
	s_or_b64 exec, exec, s[2:3]
	v_mov_b32_e32 v46, 0
	v_mov_b32_e32 v47, 0
	v_mov_b32_e32 v48, 0
	v_mov_b32_e32 v49, 0
	v_mov_b32_e32 v82, 0
	v_mov_b32_e32 v83, 0
	v_mov_b32_e32 v84, 0
	v_mov_b32_e32 v85, 0
	s_and_saveexec_b64 s[2:3], s[40:41]
	s_cbranch_execz .LBB0_929
	v_mov_b64_e32 v[42:43], s[78:79]
	v_mad_i64_i32 v[44:45], s[14:15], v125, s5, v[42:43]
	v_mov_b32_e32 v127, v1
	v_lshl_add_u64 v[44:45], v[44:45], 0, v[126:127]
	v_add_co_u32_e32 v44, vcc, 0x3000, v44
	v_mad_i64_i32 v[42:43], s[14:15], v0, s5, v[42:43]
	s_nop 0
	v_addc_co_u32_e32 v45, vcc, 0, v45, vcc
	v_lshl_add_u64 v[42:43], v[42:43], 0, v[126:127]
	v_add_co_u32_e32 v42, vcc, 0x3000, v42
	s_nop 1
	v_addc_co_u32_e32 v43, vcc, 0, v43, vcc
	v_readlane_b32 s14, v251, 20
	v_readlane_b32 s15, v251, 21
	v_add_lshl_u32 v44, v126, v157, 4
	v_lshrrev_b32_e32 v45, 4, v125
	v_lshl_add_u32 v44, v45, 10, v44
	s_nop 4
	global_load_dwordx4 v[46:49], v44, s[14:15]
	global_load_dwordx4 v[82:85], v44, s[14:15] offset:1024

; __device__ __forceinline__ void dsa_item(const KP& p, int b, int tile, char* smem) {
;     ...
;   auto scores = [&](const h8* a, float* sc) __attribute__((always_inline)) {
; #pragma unroll
;     for (int i = 0; i < 2; ++i) {
;       f32x4 acc = {0.f, 0.f, 0.f, 0.f};
;       acc = __builtin_amdgcn_mfma_f32_16x16x32_f16(a[i], qll, acc, 0, 0, 0);
;       acc = __builtin_amdgcn_mfma_f32_16x16x32_f16(a[i], qlh, acc, 0, 0, 0);
; #pragma unroll
;       for (int h = 0; h < 8; ++h) {
;         f32x4 d = {0.f, 0.f, 0.f, 0.f};
;         d = __builtin_amdgcn_mfma_f32_16x16x32_f16(a[i], qf[h], d, 0, 0, 0);
; #pragma unroll
;         for (int r = 0; r < 4; ++r) acc[r] = __builtin_fmaf(__builtin_fabsf(d[r]), iw[h], acc[r]);
;       }
; #pragma unroll
;       for (int r = 0; r < 4; ++r) sc[i * 4 + r] = acc[r];
;     }
;   };
;   auto skey = [&](float s) __attribute__((always_inline)) -> uint32_t {
;     s = s + 0.f;
;     const uint32_t u_ = __float_as_uint(s);
;     return (u_ & 0x80000000u) ? ~u_ : (u_ | 0x80000000u);
;     ...
;       for (int kt = wid; kt < nkt; kt += 4) {
;         h8 ca[2];
; #pragma unroll
;         for (int i = 0; i < 2; ++i) ca[i] = na[i];
;         loadk(kt + 4 < nkt ? kt + 4 : kt, na);
;         float sc[8];
;         scores(ca, sc);
;         if (act) {
; #pragma unroll
;           for (int q = 0; q < 8; ++q) {
;             const int key = kt * 32 + (q >> 2) * 16 + 4 * hq + (q & 3);
;             if (key <= myt) {
;               if (level < 2) {
;                 const uint32_t u32 = skey(sc[q]);
;                 if (level == 0) {
;                   const uint32_t b8 = u32 >> 24;
;                   atomicAdd(&hist[mytok * 256 + (int)b8], 1u);
;                   if (fillx) {
;                     const uint32_t ix = b8 - 0xBEu;
;                     if (ix < 3u) {
;                       const uint32_t e16 = (ix * 16u + (uint32_t)mytok) * 256u + ((u32 >> 16) & 255u);
;                       atomicAdd(&h1w[e16 >> 1], (e16 & 1u) ? 65536u : 1u);
;                     }
;                   }
;                 } else if ((u32 >> 24) == (uint32_t)mypfx) atomicAdd(&hist[mytok * 256 + (int)((u32 >> 16) & 255u)], 1u);
.LBB0_932:
	s_waitcnt vmcnt(1)
	v_mfma_f32_16x16x32_f16 v[42:45], v[46:49], v[38:41], 0
	v_mov_b32_e32 v127, v1
	v_mfma_f32_16x16x32_f16 v[86:89], v[46:49], v[34:37], v[42:45]
	s_waitcnt vmcnt(0)
	v_mfma_f32_16x16x32_f16 v[42:45], v[82:85], v[38:41], 0
	v_mfma_f32_16x16x32_f16 v[50:53], v[82:85], v[34:37], v[42:45]
	v_mfma_f32_16x16x32_f16 v[90:93], v[46:49], v[26:29], 0
	s_nop 5
	v_mov_b32_e32 v42, v153
	v_add_u32_e32 v153, 4, v42
	v_cmp_gt_i32_e32 vcc, s68, v153
	v_mfma_f32_16x16x32_f16 v[94:97], v[46:49], v[2:5], 0
	s_nop 0
	v_cndmask_b32_e32 v42, v42, v153, vcc
	v_mfma_f32_16x16x32_f16 v[98:101], v[46:49], v[6:9], 0
	v_mfma_f32_16x16x32_f16 v[102:105], v[46:49], v[10:13], 0
	v_mfma_f32_16x16x32_f16 v[106:109], v[46:49], v[14:17], 0
	v_mfma_f32_16x16x32_f16 v[110:113], v[46:49], v[18:21], 0
	v_mfma_f32_16x16x32_f16 v[114:117], v[46:49], v[22:25], 0
	v_mfma_f32_16x16x32_f16 v[118:121], v[46:49], v[30:33], 0
	v_lshl_or_b32 v46, v42, 5, v157
	v_mov_b64_e32 v[42:43], s[78:79]
	v_mad_i64_i32 v[44:45], s[2:3], v46, s5, v[42:43]
	v_lshl_add_u64 v[44:45], v[44:45], 0, v[126:127]
	v_or_b32_e32 v46, 16, v46
	v_add_co_u32_e32 v44, vcc, s23, v44
	v_mad_i64_i32 v[42:43], s[2:3], v46, s5, v[42:43]
	s_nop 0
	v_addc_co_u32_e32 v45, vcc, 0, v45, vcc
	v_lshl_add_u64 v[42:43], v[42:43], 0, v[126:127]
	v_add_co_u32_e32 v42, vcc, s23, v42
	v_mfma_f32_16x16x32_f16 v[54:57], v[82:85], v[26:29], 0
	s_nop 0
	v_addc_co_u32_e32 v43, vcc, 0, v43, vcc
	v_readlane_b32 s2, v251, 20
	v_readlane_b32 s3, v251, 21
	v_add_lshl_u32 v44, v126, v157, 4
	v_lshl_add_u32 v44, v153, 11, v44
	s_nop 4
	global_load_dwordx4 v[46:49], v44, s[2:3]
	global_load_dwordx4 v[42:45], v44, s[2:3] offset:1024
	v_mfma_f32_16x16x32_f16 v[58:61], v[82:85], v[2:5], 0
	v_cmp_le_i32_e32 vcc, s68, v153
	v_mfma_f32_16x16x32_f16 v[62:65], v[82:85], v[6:9], 0
	v_mfma_f32_16x16x32_f16 v[66:69], v[82:85], v[10:13], 0
	v_mfma_f32_16x16x32_f16 v[70:73], v[82:85], v[14:17], 0
	v_mfma_f32_16x16x32_f16 v[74:77], v[82:85], v[18:21], 0
	v_mfma_f32_16x16x32_f16 v[78:81], v[82:85], v[22:25], 0
	v_mfma_f32_16x16x32_f16 v[82:85], v[82:85], v[30:33], 0
	s_and_saveexec_b64 s[2:3], s[52:53]
	s_cbranch_execz .LBB0_931
	v_subrev_u32_e32 v127, 19, v151
	v_cmp_le_i32_e64 s[48:49], v127, v133
	s_and_saveexec_b64 s[30:31], s[48:49]
	s_cbranch_execz .LBB0_936
	v_fma_f32 v86, |v90|, v128, v86
	v_fma_f32 v86, |v94|, v130, v86
	v_fma_f32 v86, |v98|, v132, v86
	v_fma_f32 v86, |v102|, v134, v86
	v_fma_f32 v86, |v106|, v136, v86
	v_fma_f32 v86, |v110|, v138, v86
	v_fma_f32 v86, |v114|, v140, v86
	v_fma_f32 v86, |v118|, v142, v86
	v_add_f32_e32 v86, 0, v86
	v_not_b32_e32 v90, v86
	v_or_b32_e32 v94, 0x80000000, v86
	v_cmp_gt_i32_e64 s[48:49], 0, v86
	s_nop 1
	v_cndmask_b32_e64 v86, v94, v90, s[48:49]
	v_cmp_eq_u32_sdwa s[14:15], v86, v122 src0_sel:BYTE_3 src1_sel:DWORD
	s_and_b64 exec, exec, s[14:15]
	v_bfe_u32 v86, v86, 16, 8
	v_lshl_add_u32 v86, v86, 2, v123
	ds_add_u32 v86, v226
